# P9 tail tiles K-split across workgroup pairs with partial-accumulator exchange through d_ws (write-through + flag)
# speedup vs baseline: 1.0127x; 1.0127x over previous
; #define LAS __attribute__((address_space(3)))
; __global__ void __launch_bounds__(512, 2) mega_fwd(Args a) {
;     extern __shared__ __attribute__((aligned(16))) unsigned char lds_raw[];
;     LAS unsigned char* lds = (LAS unsigned char*)lds_raw;
;     cg::grid_group grid = cg::this_grid();
;     const int tid = threadIdx.x, lane = tid & 63, wave = __builtin_amdgcn_readfirstlane(tid >> 6);
;     const int G = gridDim.x, bx = blockIdx.x, gw = bx * 8 + wave, NGW = G * 8;
;     bf16_t* Hb = (bf16_t*)(a.ws + WS_H); bf16_t* proj = (bf16_t*)(a.ws + WS_PROJ); float* ssq = (float*)(a.ws + WS_SSQ);
;     const float* modall = (const float*)(a.ws + WS_MOD);
;     for (int w = bx * 512 + tid; w < XCD_BAR_WORDS; w += G * 512) __hip_atomic_store((unsigned*)(a.ws + WS_CTL) + w, 0u, __ATOMIC_RELAXED, __HIP_MEMORY_SCOPE_AGENT);
_Z8mega_fwd4Args:
	s_load_dword s51, s[0:1], 0xf8
	s_load_dwordx4 s[24:27], s[0:1], 0xe0
	s_load_dwordx2 s[6:7], s[0:1], 0xf0
	s_load_dwordx8 s[36:43], s[0:1], 0xc0
	s_add_u32 s4, s0, 0xf0
	s_addc_u32 s5, s1, 0
	v_and_b32_e32 v166, 0x3ff, v0
	s_waitcnt lgkmcnt(0)
	v_writelane_b32 v252, s6, 0
	v_readfirstlane_b32 s3, v166
	s_mov_b32 s52, s2
	v_writelane_b32 v252, s7, 1
	s_lshl_b32 s6, s2, 9
	s_mov_b32 s2, s6
	v_writelane_b32 v252, s2, 2
	v_or_b32_e32 v1, s6, v166
	s_movk_i32 s6, 0x1000
	v_writelane_b32 v252, s3, 3
	v_cmp_gt_i32_e32 vcc, s6, v1
	s_and_saveexec_b64 s[6:7], vcc
	s_cbranch_execz .LBB0_3
	s_load_dwordx2 s[8:9], s[0:1], 0xf0
	v_readlane_b32 s10, v252, 2
	v_readlane_b32 s11, v252, 3
	s_ashr_i32 s11, s10, 31
	v_mov_b32_e32 v167, 0
	s_waitcnt lgkmcnt(0)
	s_lshl_b32 s8, s8, 9
	s_mov_b32 s2, s10
	v_lshl_add_u64 v[2:3], s[10:11], 0, v[166:167]
	v_writelane_b32 v252, s2, 2
	v_lshl_add_u64 v[2:3], v[2:3], 2, s[26:27]
	s_mov_b64 s[10:11], 0x1d780000
	s_ashr_i32 s9, s8, 31
	v_writelane_b32 v252, s3, 3
	v_lshl_add_u64 v[2:3], v[2:3], 0, s[10:11]
	s_lshl_b64 s[10:11], s[8:9], 2
	s_mov_b64 s[12:13], 0
	s_movk_i32 s9, 0xfff

;     __device__ __forceinline__ const char* Ap(int part) const { return (const char*)A0 + (long)(part == 1) * ((const char*)A1 - (const char*)A0) + (long)(part == 2) * ((const char*)A2 - (const char*)A0); }
;     __device__ __forceinline__ const char* Bp(int part) const { return (const char*)B0 + (long)(part == 1) * ((const char*)B1 - (const char*)B0) + (long)(part == 2) * ((const char*)B2 - (const char*)B0); }
; template <class Epi, bool GS = false>
; __device__ __forceinline__ void gemm_phase(LAS unsigned char* lds, const Gemm g, const StaticOrder& S, const Epi& E, const int tid) {
;     ...
;         const char* nA = has_next ? g.Ap(nxt.part) + (size_t)nxt.pm * tstepA : cA; const char* nB = has_next ? g.Bp(nxt.part) + (size_t)nxt.pn * tstepB : cB;
;         const int nt = g.Kp(cur.part) / BK;
;         const int seg = (GS && cur.part == 0) ? 8 : nt;
;         for (int tg = 0; tg < nt; tg += seg) {
;         for (int t = tg; t < tg + seg; t += 2) {
;     ...
; #pragma unroll
;         for (int a = 0; a < 2; ++a)
; #pragma unroll
;             for (int b = 0; b < 2; ++b)
; #pragma unroll
;                 for (int m = 0; m < 4; ++m)
; #pragma unroll
;                     for (int n = 0; n < 2; ++n) acc[a][b][m][n] = (f32x4){0.f, 0.f, 0.f, 0.f};
.LBB0_988:
	s_nop 0
	v_cndmask_b32_e64 v0, 0, 1, s[6:7]
	v_cmp_ne_u32_e64 s[4:5], 1, v0
	s_andn2_b64 vcc, exec, s[6:7]
	s_mov_b64 s[6:7], s[20:21]
	s_cbranch_vccnz .LBB0_990
	s_mul_i32 s6, s47, 0x160000
	s_mul_hi_i32 s7, s47, 0x160000
	s_add_u32 s6, s18, s6
	s_addc_u32 s7, s19, s7
	s_cmp_eq_u32 s101, 2
	s_cbranch_scc0 .Lks9_a
	s_add_u32 s6, s6, 0xb00
	s_addc_u32 s7, s7, 0
.Lks9_a:
.LBB0_990:
	s_and_b64 vcc, exec, s[4:5]
	s_mov_b64 s[16:17], s[22:23]
	s_cbranch_vccnz .LBB0_992
	s_mul_i32 s16, s46, 0x160000
	s_mul_hi_i32 s17, s46, 0x160000
	s_add_u32 s16, s2, s16
	s_addc_u32 s17, s3, s17
	s_cmp_eq_u32 s101, 2
	s_cbranch_scc0 .Lks9_b
	s_add_u32 s16, s16, 0xb00
	s_addc_u32 s17, s17, 0
.Lks9_b:
.LBB0_992:
	s_add_u32 s50, s22, 0x100
	v_mov_b32_e32 v2, 0
	s_addc_u32 s51, s23, 0
	s_mov_b32 s52, -2
	s_cmp_eq_u32 s100, 0
	s_cselect_b32 s52, s52, 20
	v_mov_b32_e32 v3, v2
	v_mov_b32_e32 v4, v2
	v_mov_b32_e32 v5, v2
	v_mov_b32_e32 v6, v2
	v_mov_b32_e32 v7, v2
	v_mov_b32_e32 v8, v2
	v_mov_b32_e32 v9, v2
	v_mov_b32_e32 v18, v2
	v_mov_b32_e32 v19, v2
	v_mov_b32_e32 v20, v2
	v_mov_b32_e32 v21, v2
	v_mov_b32_e32 v22, v2
	v_mov_b32_e32 v23, v2
	v_mov_b32_e32 v24, v2
	v_mov_b32_e32 v25, v2
	v_mov_b32_e32 v34, v2
	v_mov_b32_e32 v35, v2
	v_mov_b32_e32 v36, v2
	v_mov_b32_e32 v37, v2
	v_mov_b32_e32 v38, v2
	v_mov_b32_e32 v39, v2
	v_mov_b32_e32 v40, v2
	v_mov_b32_e32 v41, v2
	v_mov_b32_e32 v50, v2
	v_mov_b32_e32 v51, v2
	v_mov_b32_e32 v52, v2
	v_mov_b32_e32 v53, v2
	v_mov_b32_e32 v54, v2
	v_mov_b32_e32 v55, v2
	v_mov_b32_e32 v56, v2
	v_mov_b32_e32 v57, v2
	v_mov_b32_e32 v10, v2
	v_mov_b32_e32 v11, v2
	v_mov_b32_e32 v12, v2
	v_mov_b32_e32 v13, v2
	v_mov_b32_e32 v14, v2
	v_mov_b32_e32 v15, v2
	v_mov_b32_e32 v16, v2
	v_mov_b32_e32 v17, v2
	v_mov_b32_e32 v26, v2
	v_mov_b32_e32 v27, v2
	v_mov_b32_e32 v28, v2
	v_mov_b32_e32 v29, v2
	v_mov_b32_e32 v30, v2
	v_mov_b32_e32 v31, v2
	v_mov_b32_e32 v32, v2
	v_mov_b32_e32 v33, v2
	v_mov_b32_e32 v42, v2
	v_mov_b32_e32 v43, v2
	v_mov_b32_e32 v44, v2
	v_mov_b32_e32 v45, v2
	v_mov_b32_e32 v46, v2
	v_mov_b32_e32 v47, v2
	v_mov_b32_e32 v48, v2
	v_mov_b32_e32 v49, v2
	v_mov_b32_e32 v58, v2
	v_mov_b32_e32 v59, v2
	v_mov_b32_e32 v60, v2
	v_mov_b32_e32 v61, v2
	v_mov_b32_e32 v62, v2
	v_mov_b32_e32 v63, v2
	v_mov_b32_e32 v64, v2
	v_mov_b32_e32 v65, v2
	v_mov_b32_e32 v66, v2
	v_mov_b32_e32 v67, v2
	v_mov_b32_e32 v68, v2
	v_mov_b32_e32 v69, v2
	v_mov_b32_e32 v70, v2
	v_mov_b32_e32 v71, v2
	v_mov_b32_e32 v72, v2
	v_mov_b32_e32 v73, v2
	v_mov_b32_e32 v82, v2
	v_mov_b32_e32 v83, v2
	v_mov_b32_e32 v84, v2
	v_mov_b32_e32 v85, v2
	v_mov_b32_e32 v86, v2
	v_mov_b32_e32 v87, v2
	v_mov_b32_e32 v88, v2
	v_mov_b32_e32 v89, v2
	v_mov_b32_e32 v98, v2
	v_mov_b32_e32 v99, v2
	v_mov_b32_e32 v100, v2
	v_mov_b32_e32 v101, v2
	v_mov_b32_e32 v102, v2
	v_mov_b32_e32 v103, v2
	v_mov_b32_e32 v104, v2
	v_mov_b32_e32 v105, v2
	v_mov_b32_e32 v114, v2
	v_mov_b32_e32 v115, v2
	v_mov_b32_e32 v116, v2
	v_mov_b32_e32 v117, v2
	v_mov_b32_e32 v118, v2
	v_mov_b32_e32 v119, v2
	v_mov_b32_e32 v120, v2
	v_mov_b32_e32 v121, v2
	v_mov_b32_e32 v74, v2
	v_mov_b32_e32 v75, v2
	v_mov_b32_e32 v76, v2
	v_mov_b32_e32 v77, v2
	v_mov_b32_e32 v78, v2
	v_mov_b32_e32 v79, v2
	v_mov_b32_e32 v80, v2
	v_mov_b32_e32 v81, v2
	v_mov_b32_e32 v90, v2
	v_mov_b32_e32 v91, v2
	v_mov_b32_e32 v92, v2
	v_mov_b32_e32 v93, v2
	v_mov_b32_e32 v94, v2
	v_mov_b32_e32 v95, v2
	v_mov_b32_e32 v96, v2
	v_mov_b32_e32 v97, v2
	v_mov_b32_e32 v106, v2
	v_mov_b32_e32 v107, v2
	v_mov_b32_e32 v108, v2
	v_mov_b32_e32 v109, v2
	v_mov_b32_e32 v110, v2
	v_mov_b32_e32 v111, v2
	v_mov_b32_e32 v112, v2
	v_mov_b32_e32 v113, v2
	v_mov_b32_e32 v122, v2
	v_mov_b32_e32 v123, v2
	v_mov_b32_e32 v124, v2
	v_mov_b32_e32 v125, v2
	v_mov_b32_e32 v126, v2
	v_mov_b32_e32 v127, v2
	v_mov_b32_e32 v128, v2
	v_mov_b32_e32 v129, v2

; #define PG8_BAR __builtin_amdgcn_s_barrier()
; template <class Epi, bool GS = false>
; __device__ __forceinline__ void gemm_phase(LAS unsigned char* lds, const Gemm g, const StaticOrder& S, const Epi& E, const int tid) {
;     ...
;         }
;         if (wr == 0) PG8_BAR;
;         E(acc, cur, wr, wc, fr, fq);
.LBB0_996:
	s_cmp_eq_u32 s100, 0
	s_cbranch_scc1 .Lks9_done
	v_readlane_b32 s28, v252, 2
	s_lshr_b32 s28, s28, 9
	s_lshl_b32 s29, s28, 17
	s_xor_b32 s30, s28, 1
	s_lshl_b32 s31, s30, 17
	v_lshlrev_b32_e32 v130, 4, v166
	v_add_u32_e32 v131, s31, v130
	v_add_u32_e32 v130, s29, v130
	s_cmp_eq_u32 s100, 1
	s_cbranch_scc0 .Lks9_send1
	global_store_dwordx4 v130, v[2:5], s[12:13] sc0 sc1
	v_add_u32_e32 v130, 0x2000, v130
	global_store_dwordx4 v130, v[6:9], s[12:13] sc0 sc1
	v_add_u32_e32 v130, 0x2000, v130
	global_store_dwordx4 v130, v[10:13], s[12:13] sc0 sc1
	v_add_u32_e32 v130, 0x2000, v130
	global_store_dwordx4 v130, v[14:17], s[12:13] sc0 sc1
	v_add_u32_e32 v130, 0x2000, v130
	global_store_dwordx4 v130, v[18:21], s[12:13] sc0 sc1
	v_add_u32_e32 v130, 0x2000, v130
	global_store_dwordx4 v130, v[22:25], s[12:13] sc0 sc1
	v_add_u32_e32 v130, 0x2000, v130
	global_store_dwordx4 v130, v[26:29], s[12:13] sc0 sc1
	v_add_u32_e32 v130, 0x2000, v130
	global_store_dwordx4 v130, v[30:33], s[12:13] sc0 sc1
	v_add_u32_e32 v130, 0x2000, v130
	global_store_dwordx4 v130, v[34:37], s[12:13] sc0 sc1
	v_add_u32_e32 v130, 0x2000, v130
	global_store_dwordx4 v130, v[38:41], s[12:13] sc0 sc1
	v_add_u32_e32 v130, 0x2000, v130
	global_store_dwordx4 v130, v[42:45], s[12:13] sc0 sc1
	v_add_u32_e32 v130, 0x2000, v130
	global_store_dwordx4 v130, v[46:49], s[12:13] sc0 sc1
	v_add_u32_e32 v130, 0x2000, v130
	global_store_dwordx4 v130, v[50:53], s[12:13] sc0 sc1
	v_add_u32_e32 v130, 0x2000, v130
	global_store_dwordx4 v130, v[54:57], s[12:13] sc0 sc1
	v_add_u32_e32 v130, 0x2000, v130
	global_store_dwordx4 v130, v[58:61], s[12:13] sc0 sc1
	v_add_u32_e32 v130, 0x2000, v130
	global_store_dwordx4 v130, v[62:65], s[12:13] sc0 sc1
	v_add_u32_e32 v130, 0x2000, v130
	s_branch .Lks9_sent
.Lks9_send1:
	global_store_dwordx4 v130, v[66:69], s[12:13] sc0 sc1
	v_add_u32_e32 v130, 0x2000, v130
	global_store_dwordx4 v130, v[70:73], s[12:13] sc0 sc1
	v_add_u32_e32 v130, 0x2000, v130
	global_store_dwordx4 v130, v[74:77], s[12:13] sc0 sc1
	v_add_u32_e32 v130, 0x2000, v130
	global_store_dwordx4 v130, v[78:81], s[12:13] sc0 sc1
	v_add_u32_e32 v130, 0x2000, v130
	global_store_dwordx4 v130, v[82:85], s[12:13] sc0 sc1
	v_add_u32_e32 v130, 0x2000, v130
	global_store_dwordx4 v130, v[86:89], s[12:13] sc0 sc1
	v_add_u32_e32 v130, 0x2000, v130
	global_store_dwordx4 v130, v[90:93], s[12:13] sc0 sc1
	v_add_u32_e32 v130, 0x2000, v130
	global_store_dwordx4 v130, v[94:97], s[12:13] sc0 sc1
	v_add_u32_e32 v130, 0x2000, v130
	global_store_dwordx4 v130, v[98:101], s[12:13] sc0 sc1
	v_add_u32_e32 v130, 0x2000, v130
	global_store_dwordx4 v130, v[102:105], s[12:13] sc0 sc1
	v_add_u32_e32 v130, 0x2000, v130
	global_store_dwordx4 v130, v[106:109], s[12:13] sc0 sc1
	v_add_u32_e32 v130, 0x2000, v130
	global_store_dwordx4 v130, v[110:113], s[12:13] sc0 sc1
	v_add_u32_e32 v130, 0x2000, v130
	global_store_dwordx4 v130, v[114:117], s[12:13] sc0 sc1
	v_add_u32_e32 v130, 0x2000, v130
	global_store_dwordx4 v130, v[118:121], s[12:13] sc0 sc1
	v_add_u32_e32 v130, 0x2000, v130
	global_store_dwordx4 v130, v[122:125], s[12:13] sc0 sc1
	v_add_u32_e32 v130, 0x2000, v130
	global_store_dwordx4 v130, v[126:129], s[12:13] sc0 sc1
	v_add_u32_e32 v130, 0x2000, v130
.Lks9_sent:
	s_waitcnt vmcnt(0)
	s_barrier
	v_readfirstlane_b32 s50, v166
	s_nop 0
	s_cmp_lt_u32 s50, 64
	s_cbranch_scc0 .Lks9_wait
	s_lshl_b32 s51, s30, 2
	s_addk_i32 s51, 0x3600
	v_mov_b32_e32 v132, s51
	v_mov_b32_e32 v133, 1
	s_lshl_b32 s51, s28, 2
	s_addk_i32 s51, 0x3600
	v_mov_b32_e32 v134, s51
	s_add_u32 s54, s26, 0x1d780000
	s_addc_u32 s55, s27, 0
	global_store_dword v132, v133, s[54:55] sc0 sc1
	s_mov_b32 s53, 0
.Lks9_poll:
	global_load_dword v135, v134, s[54:55] sc0 sc1
	s_waitcnt vmcnt(0)
	v_readfirstlane_b32 s52, v135
	s_add_i32 s53, s53, 1
	s_cmp_eq_u32 s52, 1
	s_cbranch_scc1 .Lks9_got
	s_sleep 1
	s_cmp_lt_u32 s53, 0x8000
	s_cbranch_scc1 .Lks9_poll
.Lks9_got:
	global_store_dword v134, v1, s[54:55] sc0 sc1
	s_waitcnt vmcnt(0)
.Lks9_wait:
	s_barrier
	s_cmp_eq_u32 s100, 1
	s_cbranch_scc0 .Lks9_recv1
	global_load_dwordx4 v[2:5], v131, s[12:13] sc0 sc1
	v_add_u32_e32 v131, 0x2000, v131
	global_load_dwordx4 v[6:9], v131, s[12:13] sc0 sc1
	v_add_u32_e32 v131, 0x2000, v131
	global_load_dwordx4 v[10:13], v131, s[12:13] sc0 sc1
	v_add_u32_e32 v131, 0x2000, v131
	global_load_dwordx4 v[14:17], v131, s[12:13] sc0 sc1
	v_add_u32_e32 v131, 0x2000, v131
	global_load_dwordx4 v[18:21], v131, s[12:13] sc0 sc1
	v_add_u32_e32 v131, 0x2000, v131
	global_load_dwordx4 v[22:25], v131, s[12:13] sc0 sc1
	v_add_u32_e32 v131, 0x2000, v131
	global_load_dwordx4 v[26:29], v131, s[12:13] sc0 sc1
	v_add_u32_e32 v131, 0x2000, v131
	global_load_dwordx4 v[30:33], v131, s[12:13] sc0 sc1
	v_add_u32_e32 v131, 0x2000, v131
	global_load_dwordx4 v[34:37], v131, s[12:13] sc0 sc1
	v_add_u32_e32 v131, 0x2000, v131
	global_load_dwordx4 v[38:41], v131, s[12:13] sc0 sc1
	v_add_u32_e32 v131, 0x2000, v131
	global_load_dwordx4 v[42:45], v131, s[12:13] sc0 sc1
	v_add_u32_e32 v131, 0x2000, v131
	global_load_dwordx4 v[46:49], v131, s[12:13] sc0 sc1
	v_add_u32_e32 v131, 0x2000, v131
	global_load_dwordx4 v[50:53], v131, s[12:13] sc0 sc1
	v_add_u32_e32 v131, 0x2000, v131
	global_load_dwordx4 v[54:57], v131, s[12:13] sc0 sc1
	v_add_u32_e32 v131, 0x2000, v131
	global_load_dwordx4 v[58:61], v131, s[12:13] sc0 sc1
	v_add_u32_e32 v131, 0x2000, v131
	global_load_dwordx4 v[62:65], v131, s[12:13] sc0 sc1
	v_add_u32_e32 v131, 0x2000, v131
	s_waitcnt vmcnt(15)
	v_pk_add_f32 v[66:67], v[66:67], v[2:3]
	v_pk_add_f32 v[68:69], v[68:69], v[4:5]
	s_waitcnt vmcnt(14)
	v_pk_add_f32 v[70:71], v[70:71], v[6:7]
	v_pk_add_f32 v[72:73], v[72:73], v[8:9]
	s_waitcnt vmcnt(13)
; #define PG8_BAR __builtin_amdgcn_s_barrier()
; template <class Epi, bool GS = false>
; __device__ __forceinline__ void gemm_phase(LAS unsigned char* lds, const Gemm g, const StaticOrder& S, const Epi& E, const int tid) {
;     ...
;         }
;         if (wr == 0) PG8_BAR;
;         E(acc, cur, wr, wc, fr, fq);
	v_pk_add_f32 v[74:75], v[74:75], v[10:11]
	v_pk_add_f32 v[76:77], v[76:77], v[12:13]
	s_waitcnt vmcnt(12)
	v_pk_add_f32 v[78:79], v[78:79], v[14:15]
	v_pk_add_f32 v[80:81], v[80:81], v[16:17]
	s_waitcnt vmcnt(11)
	v_pk_add_f32 v[82:83], v[82:83], v[18:19]
	v_pk_add_f32 v[84:85], v[84:85], v[20:21]
	s_waitcnt vmcnt(10)
	v_pk_add_f32 v[86:87], v[86:87], v[22:23]
	v_pk_add_f32 v[88:89], v[88:89], v[24:25]
	s_waitcnt vmcnt(9)
	v_pk_add_f32 v[90:91], v[90:91], v[26:27]
	v_pk_add_f32 v[92:93], v[92:93], v[28:29]
	s_waitcnt vmcnt(8)
	v_pk_add_f32 v[94:95], v[94:95], v[30:31]
	v_pk_add_f32 v[96:97], v[96:97], v[32:33]
	s_waitcnt vmcnt(7)
	v_pk_add_f32 v[98:99], v[98:99], v[34:35]
	v_pk_add_f32 v[100:101], v[100:101], v[36:37]
	s_waitcnt vmcnt(6)
	v_pk_add_f32 v[102:103], v[102:103], v[38:39]
	v_pk_add_f32 v[104:105], v[104:105], v[40:41]
	s_waitcnt vmcnt(5)
	v_pk_add_f32 v[106:107], v[106:107], v[42:43]
	v_pk_add_f32 v[108:109], v[108:109], v[44:45]
	s_waitcnt vmcnt(4)
	v_pk_add_f32 v[110:111], v[110:111], v[46:47]
	v_pk_add_f32 v[112:113], v[112:113], v[48:49]
	s_waitcnt vmcnt(3)
	v_pk_add_f32 v[114:115], v[114:115], v[50:51]
	v_pk_add_f32 v[116:117], v[116:117], v[52:53]
	s_waitcnt vmcnt(2)
	v_pk_add_f32 v[118:119], v[118:119], v[54:55]
	v_pk_add_f32 v[120:121], v[120:121], v[56:57]
	s_waitcnt vmcnt(1)
	v_pk_add_f32 v[122:123], v[122:123], v[58:59]
	v_pk_add_f32 v[124:125], v[124:125], v[60:61]
	s_waitcnt vmcnt(0)
	v_pk_add_f32 v[126:127], v[126:127], v[62:63]
	v_pk_add_f32 v[128:129], v[128:129], v[64:65]
	s_branch .Lks9_done
.Lks9_recv1:
	global_load_dwordx4 v[66:69], v131, s[12:13] sc0 sc1
	v_add_u32_e32 v131, 0x2000, v131
	global_load_dwordx4 v[70:73], v131, s[12:13] sc0 sc1
	v_add_u32_e32 v131, 0x2000, v131
	global_load_dwordx4 v[74:77], v131, s[12:13] sc0 sc1
	v_add_u32_e32 v131, 0x2000, v131
	global_load_dwordx4 v[78:81], v131, s[12:13] sc0 sc1
	v_add_u32_e32 v131, 0x2000, v131
	global_load_dwordx4 v[82:85], v131, s[12:13] sc0 sc1
	v_add_u32_e32 v131, 0x2000, v131
	global_load_dwordx4 v[86:89], v131, s[12:13] sc0 sc1
	v_add_u32_e32 v131, 0x2000, v131
	global_load_dwordx4 v[90:93], v131, s[12:13] sc0 sc1
	v_add_u32_e32 v131, 0x2000, v131
	global_load_dwordx4 v[94:97], v131, s[12:13] sc0 sc1
	v_add_u32_e32 v131, 0x2000, v131
	global_load_dwordx4 v[98:101], v131, s[12:13] sc0 sc1
	v_add_u32_e32 v131, 0x2000, v131
	global_load_dwordx4 v[102:105], v131, s[12:13] sc0 sc1
	v_add_u32_e32 v131, 0x2000, v131
	global_load_dwordx4 v[106:109], v131, s[12:13] sc0 sc1
	v_add_u32_e32 v131, 0x2000, v131
	global_load_dwordx4 v[110:113], v131, s[12:13] sc0 sc1
	v_add_u32_e32 v131, 0x2000, v131
	global_load_dwordx4 v[114:117], v131, s[12:13] sc0 sc1
	v_add_u32_e32 v131, 0x2000, v131
	global_load_dwordx4 v[118:121], v131, s[12:13] sc0 sc1
	v_add_u32_e32 v131, 0x2000, v131
	global_load_dwordx4 v[122:125], v131, s[12:13] sc0 sc1
	v_add_u32_e32 v131, 0x2000, v131
	global_load_dwordx4 v[126:129], v131, s[12:13] sc0 sc1
	v_add_u32_e32 v131, 0x2000, v131
	s_waitcnt vmcnt(15)
	v_pk_add_f32 v[2:3], v[2:3], v[66:67]
	v_pk_add_f32 v[4:5], v[4:5], v[68:69]
	s_waitcnt vmcnt(14)
	v_pk_add_f32 v[6:7], v[6:7], v[70:71]
	v_pk_add_f32 v[8:9], v[8:9], v[72:73]
	s_waitcnt vmcnt(13)
	v_pk_add_f32 v[10:11], v[10:11], v[74:75]
	v_pk_add_f32 v[12:13], v[12:13], v[76:77]
	s_waitcnt vmcnt(12)
	v_pk_add_f32 v[14:15], v[14:15], v[78:79]
	v_pk_add_f32 v[16:17], v[16:17], v[80:81]
	s_waitcnt vmcnt(11)
	v_pk_add_f32 v[18:19], v[18:19], v[82:83]
	v_pk_add_f32 v[20:21], v[20:21], v[84:85]
	s_waitcnt vmcnt(10)
	v_pk_add_f32 v[22:23], v[22:23], v[86:87]
	v_pk_add_f32 v[24:25], v[24:25], v[88:89]
	s_waitcnt vmcnt(9)
	v_pk_add_f32 v[26:27], v[26:27], v[90:91]
	v_pk_add_f32 v[28:29], v[28:29], v[92:93]
	s_waitcnt vmcnt(8)
	v_pk_add_f32 v[30:31], v[30:31], v[94:95]
	v_pk_add_f32 v[32:33], v[32:33], v[96:97]
	s_waitcnt vmcnt(7)
	v_pk_add_f32 v[34:35], v[34:35], v[98:99]
	v_pk_add_f32 v[36:37], v[36:37], v[100:101]
	s_waitcnt vmcnt(6)
	v_pk_add_f32 v[38:39], v[38:39], v[102:103]
	v_pk_add_f32 v[40:41], v[40:41], v[104:105]
	s_waitcnt vmcnt(5)
	v_pk_add_f32 v[42:43], v[42:43], v[106:107]
	v_pk_add_f32 v[44:45], v[44:45], v[108:109]
	s_waitcnt vmcnt(4)
	v_pk_add_f32 v[46:47], v[46:47], v[110:111]
	v_pk_add_f32 v[48:49], v[48:49], v[112:113]
	s_waitcnt vmcnt(3)
	v_pk_add_f32 v[50:51], v[50:51], v[114:115]
	v_pk_add_f32 v[52:53], v[52:53], v[116:117]
	s_waitcnt vmcnt(2)
	v_pk_add_f32 v[54:55], v[54:55], v[118:119]
	v_pk_add_f32 v[56:57], v[56:57], v[120:121]
	s_waitcnt vmcnt(1)
	v_pk_add_f32 v[58:59], v[58:59], v[122:123]
	v_pk_add_f32 v[60:61], v[60:61], v[124:125]
	s_waitcnt vmcnt(0)
	v_pk_add_f32 v[62:63], v[62:63], v[126:127]
	v_pk_add_f32 v[64:65], v[64:65], v[128:129]
;     __device__ __forceinline__ void operator()(const f32x4 (&acc)[2][2][4][2], const Unit& u, int wr, int wc, int fr, int fq) const {
;         const int col0 = u.pn * BM + wc * 32 + 4 * fq;
; #pragma unroll
;         for (int ai = 0; ai < 2; ++ai) {
;             const int grb = row_base + u.pm * BM + ai * HALF + wr * 64;
;             const int seq = grb < MP ? (grb >> 11) : NPB + ((grb - MP) >> 6);
;             const float* gp = gate + (size_t)seq * (6 * DM) + col0;
;             f32x4 gv[2][2];
; #pragma unroll
;             for (int bj = 0; bj < 2; ++bj)
; #pragma unroll
;                 for (int n = 0; n < 2; ++n) gv[bj][n] = *(const f32x4*)(gp + bj * HALF + n * 16);
;             if (u.part == 0) {
; #pragma unroll
;                 for (int mp = 0; mp < 2; ++mp) {
;                 f32x4 xv[2][2][2];
; #pragma unroll
;                 for (int mm = 0; mm < 2; ++mm) { const int gr = grb + (2 * mp + mm) * 16 + fr;
;                     const float* xr = (gr < MP ? xin_p + (size_t)gr * DM : xin_s + (size_t)(gr - MP) * DM) + col0;
; #pragma unroll
;                     for (int bj = 0; bj < 2; ++bj)
; #pragma unroll
;                         for (int n = 0; n < 2; ++n) xv[mm][bj][n] = *(const f32x4*)(xr + bj * HALF + n * 16); }
; #pragma unroll
;                 for (int mm = 0; mm < 2; ++mm) { const int m = 2 * mp + mm; const int gr = grb + m * 16 + fr; float* orow = out + (size_t)gr * DM + col0;
; #pragma unroll
;                     for (int bj = 0; bj < 2; ++bj)
; #pragma unroll
;                         for (int n = 0; n < 2; ++n) *(f32x4*)(orow + bj * HALF + n * 16) = xv[mm][bj][n] + gv[bj][n] * acc[ai][bj][m][n]; }
.Lks9_done:
	s_lshl_b32 s22, s48, 8
	s_add_i32 s22, s22, s42
	s_add_i32 s21, s22, 0xffff8000
	s_lshr_b32 s21, s21, 6
	s_ashr_i32 s20, s22, 11
	s_add_i32 s21, s21, 16
	s_cmp_lt_i32 s22, 0x8000
	s_cselect_b32 s20, s20, s21
	v_lshl_or_b32 v130, s49, 8, v191
	s_mul_hi_i32 s21, s20, 0x6000
	s_mulk_i32 s20, 0x6000
	v_ashrrev_i32_e32 v131, 31, v130
	s_add_u32 s20, s40, s20
	s_addc_u32 s21, s41, s21
	v_lshlrev_b64 v[180:181], 2, v[130:131]
	v_lshl_add_u64 v[130:131], s[20:21], 0, v[180:181]
	v_or_b32_e32 v182, s22, v169
	s_mov_b32 s20, 0x8000
	v_readlane_b32 s34, v255, 0
	v_add_u32_e32 v0, 0xffff8000, v182
	v_cmp_gt_i32_e32 vcc, s20, v182
	v_readlane_b32 s35, v255, 1
	v_ashrrev_i32_e32 v183, 31, v182
	v_cndmask_b32_e32 v146, v0, v182, vcc
	v_mov_b32_e32 v0, s35
	v_mov_b32_e32 v148, s25
	v_cndmask_b32_e32 v147, 0, v183, vcc
	v_cndmask_b32_e32 v149, v0, v148, vcc
	v_mov_b32_e32 v0, s34
	v_mov_b32_e32 v148, s24
	v_cndmask_b32_e32 v148, v0, v148, vcc
	v_lshlrev_b64 v[146:147], 12, v[146:147]
	v_lshl_add_u64 v[146:147], v[148:149], 0, v[146:147]
	v_lshl_add_u64 v[146:147], v[146:147], 0, v[180:181]
	global_load_dwordx4 v[142:145], v[130:131], off
	global_load_dwordx4 v[138:141], v[130:131], off offset:64
	global_load_dwordx4 v[134:137], v[130:131], off offset:512
	s_nop 0
	global_load_dwordx4 v[130:133], v[130:131], off offset:576
	s_nop 0
	global_load_dwordx4 v[158:161], v[146:147], off
	global_load_dwordx4 v[154:157], v[146:147], off offset:64
	global_load_dwordx4 v[150:153], v[146:147], off offset:512
	s_nop 0
	global_load_dwordx4 v[146:149], v[146:147], off offset:576
	v_or_b32_e32 v186, 16, v182
	s_movk_i32 s20, 0x7fff
	v_cmp_lt_i32_e32 vcc, s20, v186
	s_and_saveexec_b64 s[20:21], vcc
	s_xor_b64 s[20:21], exec, s[20:21]
	v_add_u32_e32 v0, 0xffff8010, v182
	v_lshlrev_b64 v[184:185], 12, v[0:1]
	v_mov_b32_e32 v187, v1
	v_lshl_add_u64 v[188:189], s[34:35], 0, v[184:185]
	v_lshlrev_b64 v[184:185], 12, v[186:187]
	s_andn2_saveexec_b64 s[20:21], s[20:21]
	v_ashrrev_i32_e32 v187, 31, v186
	v_lshlrev_b64 v[184:185], 12, v[186:187]
	v_lshl_add_u64 v[188:189], s[24:25], 0, v[184:185]
	s_or_b64 exec, exec, s[20:21]
	v_lshl_add_u64 v[194:195], v[188:189], 0, v[180:181]
	global_load_dwordx4 v[186:189], v[194:195], off
	global_load_dwordx4 v[216:219], v[194:195], off offset:64
	global_load_dwordx4 v[220:223], v[194:195], off offset:512
	global_load_dwordx4 v[224:227], v[194:195], off offset:576
	v_lshlrev_b64 v[194:195], 12, v[182:183]
	s_waitcnt vmcnt(0)
	v_pk_fma_f32 v[146:147], v[114:115], v[130:131], v[146:147]
	v_or_b32_e32 v114, 32, v182
	s_mov_b32 s20, 0x8000
	v_pk_fma_f32 v[118:119], v[118:119], v[134:135], v[150:151]
	v_add_u32_e32 v0, 0xffff8020, v182
	v_lshl_add_u64 v[150:151], s[24:25], 0, v[194:195]
	v_ashrrev_i32_e32 v115, 31, v114
	v_cmp_gt_i32_e32 vcc, s20, v114
	v_pk_fma_f32 v[128:129], v[128:129], v[144:145], v[160:161]
	v_pk_fma_f32 v[126:127], v[126:127], v[142:143], v[158:159]
	v_pk_fma_f32 v[124:125], v[124:125], v[140:141], v[156:157]
	v_pk_fma_f32 v[122:123], v[122:123], v[138:139], v[154:155]
	v_pk_fma_f32 v[120:121], v[120:121], v[136:137], v[152:153]
	v_mov_b32_e32 v154, s35
	v_mov_b32_e32 v155, s25
	v_mov_b32_e32 v156, s34
	v_mov_b32_e32 v157, s24
	v_lshl_add_u64 v[150:151], v[150:151], 0, v[180:181]
	v_cndmask_b32_e32 v153, 0, v115, vcc
	v_cndmask_b32_e32 v152, v0, v114, vcc
	v_pk_fma_f32 v[148:149], v[116:117], v[132:133], v[148:149]
	v_lshl_add_u64 v[116:117], s[24:25], 0, v[184:185]
	v_cndmask_b32_e32 v155, v154, v155, vcc
	v_cndmask_b32_e32 v154, v156, v157, vcc
	s_cmp_eq_u32 s100, 2
	s_cselect_b64 exec, 0, -1
	global_store_dwordx4 v[150:151], v[126:129], off
	global_store_dwordx4 v[150:151], v[122:125], off offset:64
	global_store_dwordx4 v[150:151], v[118:121], off offset:512
	global_store_dwordx4 v[150:151], v[146:149], off offset:576
	s_mov_b64 exec, -1
	v_lshl_add_u64 v[116:117], v[116:117], 0, v[180:181]
	v_lshlrev_b64 v[118:119], 12, v[152:153]
	v_lshl_add_u64 v[118:119], v[154:155], 0, v[118:119]
	v_lshl_add_u64 v[118:119], v[118:119], 0, v[180:181]
	s_movk_i32 s20, 0x7fff
	v_pk_fma_f32 v[112:113], v[112:113], v[144:145], v[188:189]
	v_pk_fma_f32 v[110:111], v[110:111], v[142:143], v[186:187]
	v_pk_fma_f32 v[108:109], v[108:109], v[140:141], v[218:219]
	v_pk_fma_f32 v[106:107], v[106:107], v[138:139], v[216:217]
	v_pk_fma_f32 v[104:105], v[104:105], v[136:137], v[222:223]
	v_pk_fma_f32 v[102:103], v[102:103], v[134:135], v[220:221]
	v_pk_fma_f32 v[100:101], v[100:101], v[132:133], v[226:227]
	v_pk_fma_f32 v[98:99], v[98:99], v[130:131], v[224:225]
	s_cmp_eq_u32 s100, 2
	s_cselect_b64 exec, 0, -1
	global_store_dwordx4 v[116:117], v[110:113], off
	global_store_dwordx4 v[116:117], v[106:109], off offset:64
	global_store_dwordx4 v[116:117], v[102:105], off offset:512
	global_store_dwordx4 v[116:117], v[98:101], off offset:576
	s_mov_b64 exec, -1
	global_load_dwordx4 v[110:113], v[118:119], off
	s_nop 0
	global_load_dwordx4 v[106:109], v[118:119], off offset:64
	global_load_dwordx4 v[102:105], v[118:119], off offset:512
	global_load_dwordx4 v[98:101], v[118:119], off offset:576
	v_or_b32_e32 v118, 48, v182
	v_cmp_lt_i32_e32 vcc, s20, v118
	s_and_saveexec_b64 s[20:21], vcc
	s_xor_b64 s[20:21], exec, s[20:21]
	v_add_u32_e32 v0, 0xffff8030, v182
	v_lshlrev_b64 v[116:117], 12, v[0:1]
	v_mov_b32_e32 v119, v1
	v_lshl_add_u64 v[120:121], s[34:35], 0, v[116:117]
	v_lshlrev_b64 v[116:117], 12, v[118:119]
	s_andn2_saveexec_b64 s[20:21], s[20:21]
	v_ashrrev_i32_e32 v119, 31, v118
	v_lshlrev_b64 v[116:117], 12, v[118:119]
	v_lshl_add_u64 v[120:121], s[24:25], 0, v[116:117]
	s_or_b64 exec, exec, s[20:21]
	v_lshl_add_u64 v[146:147], v[120:121], 0, v[180:181]
	global_load_dwordx4 v[118:121], v[146:147], off
	global_load_dwordx4 v[122:125], v[146:147], off offset:64
	global_load_dwordx4 v[126:129], v[146:147], off offset:512
	s_nop 0
	global_load_dwordx4 v[146:149], v[146:147], off offset:576
	s_add_i32 s20, s22, 0x80
	s_addk_i32 s22, 0x8080
	s_lshr_b32 s22, s22, 6
	v_lshlrev_b64 v[114:115], 12, v[114:115]
	s_waitcnt vmcnt(4)
;     __device__ __forceinline__ void operator()(const f32x4 (&acc)[2][2][4][2], const Unit& u, int wr, int wc, int fr, int fq) const {
;     ...
;                 for (int mp = 0; mp < 2; ++mp) {
;                 f32x4 xv[2][2][2];
; #pragma unroll
;                 for (int mm = 0; mm < 2; ++mm) { const int gr = grb + (2 * mp + mm) * 16 + fr;
;                     const float* xr = (gr < MP ? xin_p + (size_t)gr * DM : xin_s + (size_t)(gr - MP) * DM) + col0;
; #pragma unroll
;                     for (int bj = 0; bj < 2; ++bj)
; #pragma unroll
;                         for (int n = 0; n < 2; ++n) xv[mm][bj][n] = *(const f32x4*)(xr + bj * HALF + n * 16); }
; #pragma unroll
;                 for (int mm = 0; mm < 2; ++mm) { const int m = 2 * mp + mm; const int gr = grb + m * 16 + fr; float* orow = out + (size_t)gr * DM + col0;
; #pragma unroll
;                     for (int bj = 0; bj < 2; ++bj)
; #pragma unroll
;                         for (int n = 0; n < 2; ++n) *(f32x4*)(orow + bj * HALF + n * 16) = xv[mm][bj][n] + gv[bj][n] * acc[ai][bj][m][n]; }
	v_pk_fma_f32 v[82:83], v[82:83], v[130:131], v[98:99]
	v_lshl_add_u64 v[98:99], s[24:25], 0, v[116:117]
	s_ashr_i32 s21, s20, 11
	s_add_i32 s22, s22, 16
	v_pk_fma_f32 v[86:87], v[86:87], v[134:135], v[102:103]
	v_pk_fma_f32 v[84:85], v[84:85], v[132:133], v[100:101]
	v_lshl_add_u64 v[100:101], s[24:25], 0, v[114:115]
	v_lshl_add_u64 v[102:103], v[98:99], 0, v[180:181]
	v_or_b32_e32 v98, s20, v169
	s_cmp_lt_i32 s20, 0x8000
	s_mov_b32 s20, 0x8000
	v_pk_fma_f32 v[96:97], v[96:97], v[144:145], v[112:113]
	v_pk_fma_f32 v[94:95], v[94:95], v[142:143], v[110:111]
	v_pk_fma_f32 v[90:91], v[90:91], v[138:139], v[106:107]
	v_lshl_add_u64 v[100:101], v[100:101], 0, v[180:181]
	v_ashrrev_i32_e32 v99, 31, v98
	v_add_u32_e32 v107, 0xffff8000, v98
	v_cmp_gt_i32_e32 vcc, s20, v98
	s_cselect_b32 s20, s21, s22
	v_pk_fma_f32 v[92:93], v[92:93], v[140:141], v[108:109]
	v_pk_fma_f32 v[88:89], v[88:89], v[136:137], v[104:105]
	v_mov_b32_e32 v0, s35
	v_mov_b32_e32 v104, s25
	v_mov_b32_e32 v105, s34
	v_mov_b32_e32 v106, s24
	s_cmp_eq_u32 s100, 2
	s_cselect_b64 exec, 0, -1
	global_store_dwordx4 v[100:101], v[94:97], off
	global_store_dwordx4 v[100:101], v[90:93], off offset:64
	global_store_dwordx4 v[100:101], v[86:89], off offset:512
	global_store_dwordx4 v[100:101], v[82:85], off offset:576
	s_mov_b64 exec, -1
	s_mul_hi_i32 s21, s20, 0x6000
	s_mulk_i32 s20, 0x6000
	v_cndmask_b32_e32 v83, 0, v99, vcc
	v_cndmask_b32_e32 v82, v107, v98, vcc
	v_cndmask_b32_e32 v85, v0, v104, vcc
	v_cndmask_b32_e32 v84, v105, v106, vcc
	v_lshlrev_b64 v[82:83], 12, v[82:83]
	s_add_u32 s20, s40, s20
	v_lshl_add_u64 v[82:83], v[84:85], 0, v[82:83]
	s_addc_u32 s21, s41, s21
	v_lshl_add_u64 v[82:83], v[82:83], 0, v[180:181]
	v_lshl_add_u64 v[84:85], s[20:21], 0, v[180:181]
	s_movk_i32 s20, 0x7fff
	s_waitcnt vmcnt(7)
	v_pk_fma_f32 v[80:81], v[80:81], v[144:145], v[120:121]
	v_pk_fma_f32 v[78:79], v[78:79], v[142:143], v[118:119]
	s_waitcnt vmcnt(6)
	v_pk_fma_f32 v[76:77], v[76:77], v[140:141], v[124:125]
	v_pk_fma_f32 v[74:75], v[74:75], v[138:139], v[122:123]
	s_waitcnt vmcnt(5)
	v_pk_fma_f32 v[72:73], v[72:73], v[136:137], v[128:129]
	v_pk_fma_f32 v[70:71], v[70:71], v[134:135], v[126:127]
	s_waitcnt vmcnt(4)
	v_pk_fma_f32 v[68:69], v[68:69], v[132:133], v[148:149]
	v_pk_fma_f32 v[66:67], v[66:67], v[130:131], v[146:147]
	s_cmp_eq_u32 s100, 2
	s_cselect_b64 exec, 0, -1
	global_store_dwordx4 v[102:103], v[78:81], off
	global_store_dwordx4 v[102:103], v[74:77], off offset:64
	global_store_dwordx4 v[102:103], v[70:73], off offset:512
	global_store_dwordx4 v[102:103], v[66:69], off offset:576
	s_mov_b64 exec, -1
	global_load_dwordx4 v[78:81], v[84:85], off
	s_nop 0
	global_load_dwordx4 v[74:77], v[84:85], off offset:64
	global_load_dwordx4 v[70:73], v[84:85], off offset:512
	global_load_dwordx4 v[66:69], v[84:85], off offset:576
	global_load_dwordx4 v[94:97], v[82:83], off
	global_load_dwordx4 v[90:93], v[82:83], off offset:64
	global_load_dwordx4 v[86:89], v[82:83], off offset:512
	s_nop 0
	global_load_dwordx4 v[82:85], v[82:83], off offset:576
	v_or_b32_e32 v102, 16, v98
	v_cmp_lt_i32_e32 vcc, s20, v102
	s_and_saveexec_b64 s[20:21], vcc
	s_xor_b64 s[20:21], exec, s[20:21]
	v_add_u32_e32 v0, 0xffff8010, v98
	v_lshlrev_b64 v[100:101], 12, v[0:1]
	v_mov_b32_e32 v103, v1
	v_lshl_add_u64 v[104:105], s[34:35], 0, v[100:101]
	v_lshlrev_b64 v[100:101], 12, v[102:103]
	s_andn2_saveexec_b64 s[20:21], s[20:21]
	v_ashrrev_i32_e32 v103, 31, v102
	v_lshlrev_b64 v[100:101], 12, v[102:103]
	v_lshl_add_u64 v[104:105], s[24:25], 0, v[100:101]
	s_or_b64 exec, exec, s[20:21]
	v_lshl_add_u64 v[114:115], v[104:105], 0, v[180:181]
	global_load_dwordx4 v[102:105], v[114:115], off
	global_load_dwordx4 v[106:109], v[114:115], off offset:64
	global_load_dwordx4 v[110:113], v[114:115], off offset:512
	s_nop 0
	global_load_dwordx4 v[114:117], v[114:115], off offset:576
	v_lshlrev_b64 v[118:119], 12, v[98:99]
	s_waitcnt vmcnt(4)
; #define PG8_BAR __builtin_amdgcn_s_barrier()
; template <class Epi, bool GS = false>
; __device__ __forceinline__ void gemm_phase(LAS unsigned char* lds, const Gemm g, const StaticOrder& S, const Epi& E, const int tid) {
;     ...
;         if (!has_next) break;
; #pragma unroll
;         for (int a = 0; a < 2; ++a)
; #pragma unroll
;             for (int b = 0; b < 2; ++b)
; #pragma unroll
;                 for (int m = 0; m < 4; ++m)
; #pragma unroll
;                     for (int n = 0; n < 2; ++n) acc[a][b][m][n] = (f32x4){0.f, 0.f, 0.f, 0.f};
;         cur = nxt; cA = nA; cB = nB; ++ui;
;         if (wr == 1) PG8_BAR;
;     __device__ __forceinline__ void operator()(const f32x4 (&acc)[2][2][4][2], const Unit& u, int wr, int wc, int fr, int fq) const {
;     ...
;                 for (int mm = 0; mm < 2; ++mm) { const int gr = grb + (2 * mp + mm) * 16 + fr;
;                     const float* xr = (gr < MP ? xin_p + (size_t)gr * DM : xin_s + (size_t)(gr - MP) * DM) + col0;
; #pragma unroll
;                     for (int bj = 0; bj < 2; ++bj)
; #pragma unroll
;                         for (int n = 0; n < 2; ++n) xv[mm][bj][n] = *(const f32x4*)(xr + bj * HALF + n * 16); }
; #pragma unroll
;                 for (int mm = 0; mm < 2; ++mm) { const int m = 2 * mp + mm; const int gr = grb + m * 16 + fr; float* orow = out + (size_t)gr * DM + col0;
; #pragma unroll
;                     for (int bj = 0; bj < 2; ++bj)
; #pragma unroll
;                         for (int n = 0; n < 2; ++n) *(f32x4*)(orow + bj * HALF + n * 16) = xv[mm][bj][n] + gv[bj][n] * acc[ai][bj][m][n]; }
	v_pk_fma_f32 v[82:83], v[50:51], v[66:67], v[82:83]
	v_or_b32_e32 v50, 32, v98
	s_mov_b32 s20, 0x8000
	v_pk_fma_f32 v[54:55], v[54:55], v[70:71], v[86:87]
	v_add_u32_e32 v0, 0xffff8020, v98
	v_lshl_add_u64 v[86:87], s[24:25], 0, v[118:119]
	v_ashrrev_i32_e32 v51, 31, v50
	v_cmp_gt_i32_e32 vcc, s20, v50
	v_pk_fma_f32 v[64:65], v[64:65], v[80:81], v[96:97]
	v_pk_fma_f32 v[62:63], v[62:63], v[78:79], v[94:95]
	v_pk_fma_f32 v[60:61], v[60:61], v[76:77], v[92:93]
	v_pk_fma_f32 v[58:59], v[58:59], v[74:75], v[90:91]
	v_pk_fma_f32 v[56:57], v[56:57], v[72:73], v[88:89]
	v_mov_b32_e32 v90, s35
	v_mov_b32_e32 v91, s25
	v_mov_b32_e32 v92, s34
	v_mov_b32_e32 v93, s24
	v_lshl_add_u64 v[86:87], v[86:87], 0, v[180:181]
	v_cndmask_b32_e32 v89, 0, v51, vcc
	v_cndmask_b32_e32 v88, v0, v50, vcc
	v_pk_fma_f32 v[84:85], v[52:53], v[68:69], v[84:85]
	v_lshl_add_u64 v[52:53], s[24:25], 0, v[100:101]
	v_cndmask_b32_e32 v91, v90, v91, vcc
	v_cndmask_b32_e32 v90, v92, v93, vcc
	s_cmp_eq_u32 s100, 1
	s_cselect_b64 exec, 0, -1
	global_store_dwordx4 v[86:87], v[62:65], off
	global_store_dwordx4 v[86:87], v[58:61], off offset:64
	global_store_dwordx4 v[86:87], v[54:57], off offset:512
	global_store_dwordx4 v[86:87], v[82:85], off offset:576
	s_mov_b64 exec, -1
	v_lshl_add_u64 v[52:53], v[52:53], 0, v[180:181]
	v_lshlrev_b64 v[54:55], 12, v[88:89]
	v_lshl_add_u64 v[54:55], v[90:91], 0, v[54:55]
	v_lshl_add_u64 v[54:55], v[54:55], 0, v[180:181]
	s_movk_i32 s20, 0x7fff
	s_waitcnt vmcnt(7)
	v_pk_fma_f32 v[48:49], v[48:49], v[80:81], v[104:105]
	v_pk_fma_f32 v[46:47], v[46:47], v[78:79], v[102:103]
	s_waitcnt vmcnt(6)
	v_pk_fma_f32 v[44:45], v[44:45], v[76:77], v[108:109]
	v_pk_fma_f32 v[42:43], v[42:43], v[74:75], v[106:107]
	s_waitcnt vmcnt(5)
	v_pk_fma_f32 v[40:41], v[40:41], v[72:73], v[112:113]
	v_pk_fma_f32 v[38:39], v[38:39], v[70:71], v[110:111]
	s_waitcnt vmcnt(4)
	v_pk_fma_f32 v[36:37], v[36:37], v[68:69], v[116:117]
	v_pk_fma_f32 v[34:35], v[34:35], v[66:67], v[114:115]
	s_cmp_eq_u32 s100, 1
	s_cselect_b64 exec, 0, -1
	global_store_dwordx4 v[52:53], v[46:49], off
	global_store_dwordx4 v[52:53], v[42:45], off offset:64
	global_store_dwordx4 v[52:53], v[38:41], off offset:512
	global_store_dwordx4 v[52:53], v[34:37], off offset:576
	s_mov_b64 exec, -1
	global_load_dwordx4 v[46:49], v[54:55], off
	s_nop 0
	global_load_dwordx4 v[42:45], v[54:55], off offset:64
	global_load_dwordx4 v[38:41], v[54:55], off offset:512
	global_load_dwordx4 v[34:37], v[54:55], off offset:576
	v_or_b32_e32 v54, 48, v98
	v_cmp_lt_i32_e32 vcc, s20, v54
	s_and_saveexec_b64 s[20:21], vcc
	s_xor_b64 s[20:21], exec, s[20:21]
	v_add_u32_e32 v0, 0xffff8030, v98
	v_lshlrev_b64 v[52:53], 12, v[0:1]
	v_mov_b32_e32 v55, v1
	v_lshl_add_u64 v[56:57], s[34:35], 0, v[52:53]
	v_lshlrev_b64 v[52:53], 12, v[54:55]
	s_andn2_saveexec_b64 s[20:21], s[20:21]
	v_ashrrev_i32_e32 v55, 31, v54
	v_lshlrev_b64 v[52:53], 12, v[54:55]
	v_lshl_add_u64 v[56:57], s[24:25], 0, v[52:53]
	s_or_b64 exec, exec, s[20:21]
	v_lshl_add_u64 v[82:83], v[56:57], 0, v[180:181]
	global_load_dwordx4 v[54:57], v[82:83], off
	global_load_dwordx4 v[58:61], v[82:83], off offset:64
	global_load_dwordx4 v[62:65], v[82:83], off offset:512
	s_nop 0
	global_load_dwordx4 v[82:85], v[82:83], off offset:576
	v_lshlrev_b64 v[50:51], 12, v[50:51]
	s_waitcnt vmcnt(4)
	v_pk_fma_f32 v[20:21], v[20:21], v[68:69], v[36:37]
	v_pk_fma_f32 v[18:19], v[18:19], v[66:67], v[34:35]
	v_lshl_add_u64 v[34:35], s[24:25], 0, v[52:53]
	v_lshl_add_u64 v[36:37], s[24:25], 0, v[50:51]
	v_pk_fma_f32 v[32:33], v[32:33], v[80:81], v[48:49]
	v_pk_fma_f32 v[30:31], v[30:31], v[78:79], v[46:47]
	s_and_b64 vcc, exec, s[4:5]
	v_lshl_add_u64 v[34:35], v[34:35], 0, v[180:181]
	v_lshl_add_u64 v[36:37], v[36:37], 0, v[180:181]
	s_mov_b64 s[4:5], -1
	v_pk_fma_f32 v[28:29], v[28:29], v[76:77], v[44:45]
	v_pk_fma_f32 v[26:27], v[26:27], v[74:75], v[42:43]
	v_pk_fma_f32 v[24:25], v[24:25], v[72:73], v[40:41]
	v_pk_fma_f32 v[22:23], v[22:23], v[70:71], v[38:39]
	s_cmp_eq_u32 s100, 1
	s_cselect_b64 exec, 0, -1
	global_store_dwordx4 v[36:37], v[30:33], off
	global_store_dwordx4 v[36:37], v[26:29], off offset:64
	global_store_dwordx4 v[36:37], v[22:25], off offset:512
	global_store_dwordx4 v[36:37], v[18:21], off offset:576
	s_mov_b64 exec, -1
	s_waitcnt vmcnt(7)
	v_pk_fma_f32 v[16:17], v[16:17], v[80:81], v[56:57]
	v_pk_fma_f32 v[14:15], v[14:15], v[78:79], v[54:55]
	s_waitcnt vmcnt(6)
	v_pk_fma_f32 v[12:13], v[12:13], v[76:77], v[60:61]
	v_pk_fma_f32 v[10:11], v[10:11], v[74:75], v[58:59]
	s_waitcnt vmcnt(5)
	v_pk_fma_f32 v[8:9], v[8:9], v[72:73], v[64:65]
	v_pk_fma_f32 v[6:7], v[6:7], v[70:71], v[62:63]
	s_waitcnt vmcnt(4)
	v_pk_fma_f32 v[4:5], v[4:5], v[68:69], v[84:85]
	v_pk_fma_f32 v[2:3], v[2:3], v[66:67], v[82:83]
	s_cmp_eq_u32 s100, 1
	s_cselect_b64 exec, 0, -1
	global_store_dwordx4 v[34:35], v[14:17], off
	global_store_dwordx4 v[34:35], v[10:13], off offset:64
	global_store_dwordx4 v[34:35], v[6:9], off offset:512
	global_store_dwordx4 v[34:35], v[2:5], off offset:576
	s_mov_b64 exec, -1
	s_cbranch_vccnz .LBB0_985
	s_andn2_b64 vcc, exec, s[8:9]
	s_cbranch_vccnz .LBB0_984
	s_barrier
	s_branch .LBB0_984
